# pool mixer: waves 4-7 start about 3 us late so the two waves of a SIMD alternate load-wait and compute
# speedup vs baseline: 1.0001x; 1.0001x over previous
.LBB0_107:
	s_and_b64 vcc, exec, s[2:3]
	s_cbranch_vccz .LBB0_364
	v_readlane_b32 s2, v252, 30
	v_readlane_b32 s3, v252, 31
	s_lshl_b32 s2, s2, 10
	s_ashr_i32 s3, s2, 31
	v_readlane_b32 s6, v252, 24
	s_load_dwordx2 s[4:5], s[0:1], 0x60
	v_readlane_b32 s7, v252, 25
	s_add_u32 s6, s6, 0x13200000
	s_addc_u32 s7, s7, 0
	s_waitcnt lgkmcnt(0)
	s_add_u32 s8, s14, 0x1b300000
	s_addc_u32 s9, s15, 0
	s_lshl_b64 s[2:3], s[2:3], 2
	s_add_u32 s2, s4, s2
	s_load_dwordx2 s[16:17], s[0:1], 0x98
	s_waitcnt vmcnt(0)
	v_mov_b32 v155, v210
	s_addc_u32 s3, s5, s3
	v_readfirstlane_b32 s4, v155
	v_lshlrev_b32_e32 v0, 3, v155
	s_bfe_u32 s26, s4, 0x20006
	s_bitcmp1_b32 s4, 8
	s_cbranch_scc0 .Lpool_nodelay
	s_sleep 100
.Lpool_nodelay:
	v_and_b32_e32 v0, 0xf8, v0
	v_lshl_or_b32 v9, s26, 8, v0
	v_lshlrev_b32_e32 v4, 2, v9
	global_load_dwordx4 v[0:3], v4, s[2:3] offset:16
	s_nop 0
	global_load_dwordx4 v[4:7], v4, s[2:3]
	s_ashr_i32 s4, s4, 7
	v_lshrrev_b32_e32 v8, 5, v155
	v_bfi_b32 v8, -2, s4, v8
	s_cmpk_gt_i32 s80, 0x7ff
	v_lshlrev_b32_e32 v153, 3, v8
	v_lshlrev_b32_e32 v96, 1, v9
	s_cbranch_scc1 .LBB0_238
	v_lshlrev_b32_e32 v161, 3, v8
	v_lshl_add_u64 v[134:135], s[12:13], 0, v[96:97]
	v_lshl_add_u64 v[136:137], s[6:7], 0, v[96:97]
	v_lshl_add_u64 v[138:139], s[8:9], 0, v[96:97]
	s_sub_i32 s5, 0x7ff, s80
	s_mov_b32 s18, s80
	s_branch .LBB0_112
